# v12 + all neutral instruction-count reductions combined (trimmed load-segment slots, fp8 barrier-first without inner waits, v_mov_b64 zero-fill)
# speedup vs baseline: 1.0037x; 1.0037x over previous
.LBB0_1420:
	ds_read_b128 v[146:149], v138
	ds_read_b128 v[150:153], v138 offset:1024
	ds_read_b128 v[154:157], v138 offset:2048
	ds_read_b128 v[158:161], v138 offset:3072
	ds_read_b128 v[162:165], v139
	ds_read_b128 v[166:169], v139 offset:1024
	ds_read_b128 v[170:173], v139 offset:2048
	ds_read_b128 v[174:177], v139 offset:3072
	s_add_i32 s14, s73, 0xfff40080
	s_cmp_eq_u32 s60, s75
	s_cselect_b32 s76, s71, s14
	s_cselect_b32 s78, s72, s74
	s_or_b32 s77, s76, 0x80
	s_add_i32 s14, s73, 0xfffc0000
	s_mov_b32 m0, s61
	ds_read_b128 v[178:181], v140
	ds_read_b128 v[182:185], v140 offset:1024
	ds_read_b128 v[186:189], v140 offset:2048
	ds_read_b128 v[190:193], v140 offset:3072
	ds_read_b128 v[194:197], v140 offset:4096
	ds_read_b128 v[198:201], v140 offset:5120
	ds_read_b128 v[202:205], v140 offset:6144
	ds_read_b128 v[206:209], v140 offset:7168
	buffer_load_dwordx4 v136, s[16:19], s14 offen lds
	s_mov_b32 m0, s62
	s_nop 0
	buffer_load_dwordx4 v136, s[16:19], s73 offen lds
	s_waitcnt vmcnt(8) lgkmcnt(0)
	s_setprio 1
	s_barrier
	v_mfma_f32_16x16x128_f8f6f4 v[118:121], v[146:153], v[178:185], v[118:121]
	v_mfma_f32_16x16x128_f8f6f4 v[114:117], v[154:161], v[178:185], v[114:117]
	v_mfma_f32_16x16x128_f8f6f4 v[110:113], v[146:153], v[186:193], v[110:113]
	v_mfma_f32_16x16x128_f8f6f4 v[102:105], v[154:161], v[186:193], v[102:105]
	v_mfma_f32_16x16x128_f8f6f4 v[126:129], v[162:169], v[178:185], v[126:129]
	v_mfma_f32_16x16x128_f8f6f4 v[122:125], v[170:177], v[178:185], v[122:125]
	v_mfma_f32_16x16x128_f8f6f4 v[106:109], v[162:169], v[186:193], v[106:109]
	v_mfma_f32_16x16x128_f8f6f4 v[98:101], v[170:177], v[186:193], v[98:101]
	v_mfma_f32_16x16x128_f8f6f4 v[210:213], v[146:153], v[194:201], v[94:97]
	v_mfma_f32_16x16x128_f8f6f4 v[214:217], v[154:161], v[194:201], v[86:89]
	v_mfma_f32_16x16x128_f8f6f4 v[218:221], v[146:153], v[202:209], v[78:81]
	v_mfma_f32_16x16x128_f8f6f4 v[222:225], v[154:161], v[202:209], v[70:73]
	v_mfma_f32_16x16x128_f8f6f4 v[178:181], v[162:169], v[194:201], v[90:93]
	v_mfma_f32_16x16x128_f8f6f4 v[182:185], v[170:177], v[194:201], v[82:85]
	v_mfma_f32_16x16x128_f8f6f4 v[186:189], v[162:169], v[202:209], v[74:77]
	v_mfma_f32_16x16x128_f8f6f4 v[190:193], v[170:177], v[202:209], v[66:69]
	s_setprio 0
	s_barrier
	s_mov_b32 m0, s31
	s_mov_b32 s14, s18
	s_mov_b32 s15, s19
	s_nop 1
	ds_read_b128 v[66:69], v140 offset:16384
	ds_read_b128 v[70:73], v140 offset:17408
	ds_read_b128 v[74:77], v140 offset:18432
	ds_read_b128 v[78:81], v140 offset:19456
	ds_read_b128 v[82:85], v140 offset:20480
	ds_read_b128 v[86:89], v140 offset:21504
	ds_read_b128 v[90:93], v140 offset:22528
	ds_read_b128 v[94:97], v140 offset:23552
	buffer_load_dwordx4 v137, s[12:15], s78 offen lds
	s_mov_b32 m0, s46
	s_add_i32 s79, s78, 0x40000
	buffer_load_dwordx4 v137, s[12:15], s79 offen lds
	s_mov_b32 m0, s47
	s_add_i32 s79, s78, 0x80000
	buffer_load_dwordx4 v137, s[12:15], s79 offen lds
	s_mov_b32 m0, s48
	s_add_i32 s79, s78, 0xc0000
	buffer_load_dwordx4 v137, s[12:15], s79 offen lds
	s_mov_b32 m0, s30
	s_add_i32 s79, s76, 0x40000
	buffer_load_dwordx4 v136, s[16:19], s76 offen lds
	s_mov_b32 m0, s49
	s_nop 0
	buffer_load_dwordx4 v136, s[16:19], s79 offen lds
	s_waitcnt vmcnt(8) lgkmcnt(0)
	s_setprio 1
	s_barrier
	v_mfma_f32_16x16x128_f8f6f4 v[62:65], v[146:153], v[66:73], v[62:65]
	v_mfma_f32_16x16x128_f8f6f4 v[54:57], v[154:161], v[66:73], v[54:57]
	v_mfma_f32_16x16x128_f8f6f4 v[46:49], v[146:153], v[74:81], v[46:49]
	v_mfma_f32_16x16x128_f8f6f4 v[58:61], v[162:169], v[66:73], v[58:61]
	v_mfma_f32_16x16x128_f8f6f4 v[50:53], v[170:177], v[66:73], v[50:53]
	v_mfma_f32_16x16x128_f8f6f4 v[42:45], v[162:169], v[74:81], v[42:45]
	v_mfma_f32_16x16x128_f8f6f4 v[202:205], v[154:161], v[74:81], v[38:41]
	v_mfma_f32_16x16x128_f8f6f4 v[206:209], v[146:153], v[82:89], v[30:33]
	v_mfma_f32_16x16x128_f8f6f4 v[226:229], v[154:161], v[82:89], v[22:25]
	v_mfma_f32_16x16x128_f8f6f4 v[230:233], v[146:153], v[90:97], v[14:17]
	v_mfma_f32_16x16x128_f8f6f4 v[234:237], v[154:161], v[90:97], v[6:9]
	v_mfma_f32_16x16x128_f8f6f4 v[238:241], v[170:177], v[74:81], v[34:37]
	v_mfma_f32_16x16x128_f8f6f4 v[242:245], v[162:169], v[82:89], v[26:29]
	v_mfma_f32_16x16x128_f8f6f4 v[246:249], v[170:177], v[82:89], v[18:21]
	v_mfma_f32_16x16x128_f8f6f4 v[250:253], v[162:169], v[90:97], v[10:13]
	v_mfma_f32_16x16x128_f8f6f4 v[130:133], v[170:177], v[90:97], v[2:5]
	s_setprio 0
	s_barrier
	s_nop 4
	ds_read_b128 v[2:5], v141
	ds_read_b128 v[6:9], v141 offset:1024
	ds_read_b128 v[146:149], v141 offset:2048
	ds_read_b128 v[150:153], v141 offset:3072
	ds_read_b128 v[154:157], v142
	ds_read_b128 v[158:161], v142 offset:1024
	ds_read_b128 v[162:165], v142 offset:2048
	ds_read_b128 v[166:169], v142 offset:3072
	s_mov_b32 m0, s50
	s_add_i32 s79, s76, 0x80000
	ds_read_b128 v[10:13], v140 offset:32768
	ds_read_b128 v[14:17], v140 offset:33792
	ds_read_b128 v[18:21], v140 offset:34816
	ds_read_b128 v[22:25], v140 offset:35840
	ds_read_b128 v[26:29], v140 offset:36864
	ds_read_b128 v[30:33], v140 offset:37888
	ds_read_b128 v[34:37], v140 offset:38912
	ds_read_b128 v[38:41], v140 offset:39936
	buffer_load_dwordx4 v136, s[16:19], s79 offen lds
	s_mov_b32 m0, s51
	s_add_i32 s79, s76, 0xc0000
	buffer_load_dwordx4 v136, s[16:19], s79 offen lds
	s_waitcnt vmcnt(8) lgkmcnt(0)
	s_setprio 1
	s_barrier
	v_mfma_f32_16x16x128_f8f6f4 v[118:121], v[2:9], v[10:17], v[118:121]
	v_mfma_f32_16x16x128_f8f6f4 v[114:117], v[146:153], v[10:17], v[114:117]
	v_mfma_f32_16x16x128_f8f6f4 v[110:113], v[2:9], v[18:25], v[110:113]
	v_mfma_f32_16x16x128_f8f6f4 v[102:105], v[146:153], v[18:25], v[102:105]
	v_mfma_f32_16x16x128_f8f6f4 v[94:97], v[2:9], v[26:33], v[210:213]
	v_mfma_f32_16x16x128_f8f6f4 v[86:89], v[146:153], v[26:33], v[214:217]
	v_mfma_f32_16x16x128_f8f6f4 v[78:81], v[2:9], v[34:41], v[218:221]
	v_mfma_f32_16x16x128_f8f6f4 v[70:73], v[146:153], v[34:41], v[222:225]
	v_mfma_f32_16x16x128_f8f6f4 v[126:129], v[154:161], v[10:17], v[126:129]
	v_mfma_f32_16x16x128_f8f6f4 v[122:125], v[162:169], v[10:17], v[122:125]
	v_mfma_f32_16x16x128_f8f6f4 v[106:109], v[154:161], v[18:25], v[106:109]
	v_mfma_f32_16x16x128_f8f6f4 v[98:101], v[162:169], v[18:25], v[98:101]
	v_mfma_f32_16x16x128_f8f6f4 v[90:93], v[154:161], v[26:33], v[178:181]
	v_mfma_f32_16x16x128_f8f6f4 v[82:85], v[162:169], v[26:33], v[182:185]
	v_mfma_f32_16x16x128_f8f6f4 v[74:77], v[154:161], v[34:41], v[186:189]
	v_mfma_f32_16x16x128_f8f6f4 v[66:69], v[162:169], v[34:41], v[190:193]
	s_setprio 0
	s_barrier
	s_mov_b32 m0, s54
	s_or_b32 s79, s78, 0x80
	ds_read_b128 v[170:173], v140 offset:49152
	ds_read_b128 v[174:177], v140 offset:50176
	ds_read_b128 v[178:181], v140 offset:51200
	ds_read_b128 v[182:185], v140 offset:52224
	ds_read_b128 v[186:189], v140 offset:53248
	ds_read_b128 v[190:193], v140 offset:54272
	ds_read_b128 v[194:197], v140 offset:55296
	ds_read_b128 v[198:201], v140 offset:56320
	buffer_load_dwordx4 v137, s[12:15], s79 offen lds
	s_add_i32 s79, s78, 0x40080
	s_mov_b32 m0, s55
	s_add_i32 s76, s76, 0x40080
	buffer_load_dwordx4 v137, s[12:15], s79 offen lds
	s_add_i32 s79, s78, 0x80080
	s_mov_b32 m0, s58
	s_add_i32 s78, s78, 0xc0080
	buffer_load_dwordx4 v137, s[12:15], s79 offen lds
	s_mov_b32 m0, s59
	s_nop 0
	buffer_load_dwordx4 v137, s[12:15], s78 offen lds
	s_mov_b32 m0, s56
	s_nop 0
	buffer_load_dwordx4 v136, s[16:19], s77 offen lds
	s_mov_b32 m0, s57
	s_nop 0
	buffer_load_dwordx4 v136, s[16:19], s76 offen lds
	s_waitcnt vmcnt(8) lgkmcnt(0)
	s_setprio 1
	s_barrier
	v_mfma_f32_16x16x128_f8f6f4 v[62:65], v[2:9], v[170:177], v[62:65]
	v_mfma_f32_16x16x128_f8f6f4 v[54:57], v[146:153], v[170:177], v[54:57]
	v_mfma_f32_16x16x128_f8f6f4 v[46:49], v[2:9], v[178:185], v[46:49]
	v_mfma_f32_16x16x128_f8f6f4 v[38:41], v[146:153], v[178:185], v[202:205]
	v_mfma_f32_16x16x128_f8f6f4 v[30:33], v[2:9], v[186:193], v[206:209]
	v_mfma_f32_16x16x128_f8f6f4 v[22:25], v[146:153], v[186:193], v[226:229]
	v_mfma_f32_16x16x128_f8f6f4 v[14:17], v[2:9], v[194:201], v[230:233]
	v_mfma_f32_16x16x128_f8f6f4 v[6:9], v[146:153], v[194:201], v[234:237]
	v_mfma_f32_16x16x128_f8f6f4 v[58:61], v[154:161], v[170:177], v[58:61]
	v_mfma_f32_16x16x128_f8f6f4 v[50:53], v[162:169], v[170:177], v[50:53]
	v_mfma_f32_16x16x128_f8f6f4 v[42:45], v[154:161], v[178:185], v[42:45]
	v_mfma_f32_16x16x128_f8f6f4 v[34:37], v[162:169], v[178:185], v[238:241]
	v_mfma_f32_16x16x128_f8f6f4 v[26:29], v[154:161], v[186:193], v[242:245]
	v_mfma_f32_16x16x128_f8f6f4 v[18:21], v[162:169], v[186:193], v[246:249]
	v_mfma_f32_16x16x128_f8f6f4 v[10:13], v[154:161], v[194:201], v[250:253]
	v_mfma_f32_16x16x128_f8f6f4 v[2:5], v[162:169], v[194:201], v[130:133]
	s_setprio 0
	s_barrier
	s_add_i32 s75, s75, 2
	s_addk_i32 s73, 0x100
	s_addk_i32 s74, 0x100
	s_cmp_ge_i32 s75, s25
	s_cbranch_scc0 .LBB0_1420
	s_and_b64 vcc, exec, s[44:45]
	s_cbranch_vccz .LBB0_1423

.LBB0_1567:
	ds_read_b128 v[134:137], v225
	ds_read_b128 v[138:141], v225 offset:1024
	ds_read_b128 v[142:145], v225 offset:2048
	ds_read_b128 v[146:149], v225 offset:3072
	ds_read_b128 v[150:153], v226
	ds_read_b128 v[154:157], v226 offset:1024
	ds_read_b128 v[158:161], v226 offset:2048
	ds_read_b128 v[162:165], v226 offset:3072
	s_add_i32 s18, s8, 0xffdfc080
	s_cmp_eq_u32 s71, s55
	s_cselect_b32 s56, s6, s18
	s_cselect_b32 s91, s7, s9
	s_or_b32 s57, s56, 0x80
	s_add_i32 s18, s8, 0xfff54000
	s_mov_b32 m0, s72
	ds_read_b128 v[166:169], v227
	ds_read_b128 v[170:173], v227 offset:1024
	ds_read_b128 v[174:177], v227 offset:2048
	ds_read_b128 v[178:181], v227 offset:3072
	ds_read_b128 v[182:185], v227 offset:4096
	ds_read_b128 v[186:189], v227 offset:5120
	ds_read_b128 v[190:193], v227 offset:6144
	ds_read_b128 v[194:197], v227 offset:7168
	buffer_load_dwordx4 v223, s[12:15], s18 offen lds
	s_mov_b32 m0, s75
	s_nop 0
	buffer_load_dwordx4 v223, s[12:15], s8 offen lds
	s_waitcnt vmcnt(8) lgkmcnt(0)
	s_setprio 1
	s_barrier
	v_mfma_f32_16x16x128_f8f6f4 v[126:129], v[134:141], v[166:173], v[126:129]
	v_mfma_f32_16x16x128_f8f6f4 v[122:125], v[142:149], v[166:173], v[122:125]
	v_mfma_f32_16x16x128_f8f6f4 v[118:121], v[134:141], v[174:181], v[118:121]
	v_mfma_f32_16x16x128_f8f6f4 v[114:117], v[142:149], v[174:181], v[114:117]
	v_mfma_f32_16x16x128_f8f6f4 v[106:109], v[134:141], v[182:189], v[106:109]
	v_mfma_f32_16x16x128_f8f6f4 v[98:101], v[142:149], v[182:189], v[98:101]
	v_mfma_f32_16x16x128_f8f6f4 v[110:113], v[150:157], v[166:173], v[110:113]
	v_mfma_f32_16x16x128_f8f6f4 v[102:105], v[158:165], v[166:173], v[102:105]
	v_mfma_f32_16x16x128_f8f6f4 v[198:201], v[134:141], v[190:197], v[90:93]
	v_mfma_f32_16x16x128_f8f6f4 v[202:205], v[142:149], v[190:197], v[82:85]
	v_mfma_f32_16x16x128_f8f6f4 v[166:169], v[150:157], v[174:181], v[94:97]
	v_mfma_f32_16x16x128_f8f6f4 v[170:173], v[158:165], v[174:181], v[86:89]
	v_mfma_f32_16x16x128_f8f6f4 v[174:177], v[150:157], v[182:189], v[78:81]
	v_mfma_f32_16x16x128_f8f6f4 v[178:181], v[158:165], v[182:189], v[74:77]
	v_mfma_f32_16x16x128_f8f6f4 v[182:185], v[150:157], v[190:197], v[70:73]
	v_mfma_f32_16x16x128_f8f6f4 v[186:189], v[158:165], v[190:197], v[66:69]
	s_setprio 0
	s_barrier
	s_mov_b32 m0, s27
	s_mov_b32 s18, s14
	s_mov_b32 s19, s15
	s_nop 1
	ds_read_b128 v[66:69], v227 offset:16384
	ds_read_b128 v[70:73], v227 offset:17408
	ds_read_b128 v[74:77], v227 offset:18432
	ds_read_b128 v[78:81], v227 offset:19456
	ds_read_b128 v[82:85], v227 offset:20480
	ds_read_b128 v[86:89], v227 offset:21504
	ds_read_b128 v[90:93], v227 offset:22528
	ds_read_b128 v[94:97], v227 offset:23552
	buffer_load_dwordx4 v224, s[16:19], s91 offen lds
	s_mov_b32 m0, s30
	s_add_i32 s92, s91, 0xac000
	buffer_load_dwordx4 v224, s[16:19], s92 offen lds
	s_mov_b32 m0, s31
	s_add_i32 s92, s91, 0x158000
	buffer_load_dwordx4 v224, s[16:19], s92 offen lds
	s_mov_b32 m0, s51
	s_add_i32 s92, s91, 0x204000
	buffer_load_dwordx4 v224, s[16:19], s92 offen lds
	s_mov_b32 m0, s25
	s_add_i32 s92, s56, 0xac000
	buffer_load_dwordx4 v223, s[12:15], s56 offen lds
	s_mov_b32 m0, s58
	s_nop 0
	buffer_load_dwordx4 v223, s[12:15], s92 offen lds
	s_waitcnt vmcnt(8) lgkmcnt(0)
	s_setprio 1
	s_barrier
	v_mfma_f32_16x16x128_f8f6f4 v[62:65], v[134:141], v[66:73], v[62:65]
	v_mfma_f32_16x16x128_f8f6f4 v[58:61], v[142:149], v[66:73], v[58:61]
	v_mfma_f32_16x16x128_f8f6f4 v[54:57], v[134:141], v[74:81], v[54:57]
	v_mfma_f32_16x16x128_f8f6f4 v[50:53], v[142:149], v[74:81], v[50:53]
	v_mfma_f32_16x16x128_f8f6f4 v[190:193], v[134:141], v[82:89], v[42:45]
	v_mfma_f32_16x16x128_f8f6f4 v[194:197], v[142:149], v[82:89], v[34:37]
	v_mfma_f32_16x16x128_f8f6f4 v[206:209], v[134:141], v[90:97], v[26:29]
	v_mfma_f32_16x16x128_f8f6f4 v[210:213], v[142:149], v[90:97], v[18:21]
	v_mfma_f32_16x16x128_f8f6f4 v[214:217], v[150:157], v[66:73], v[46:49]
	v_mfma_f32_16x16x128_f8f6f4 v[218:221], v[158:165], v[66:73], v[38:41]
	v_mfma_f32_16x16x128_f8f6f4 v[234:237], v[150:157], v[74:81], v[30:33]
	v_mfma_f32_16x16x128_f8f6f4 v[238:241], v[158:165], v[74:81], v[22:25]
	v_mfma_f32_16x16x128_f8f6f4 v[242:245], v[150:157], v[82:89], v[14:17]
	v_mfma_f32_16x16x128_f8f6f4 v[246:249], v[158:165], v[82:89], v[10:13]
	v_mfma_f32_16x16x128_f8f6f4 v[250:253], v[150:157], v[90:97], v[6:9]
	v_mfma_f32_16x16x128_f8f6f4 v[130:133], v[158:165], v[90:97], v[2:5]
	s_setprio 0
	s_barrier
	s_nop 4
	ds_read_b128 v[2:5], v228
	ds_read_b128 v[6:9], v228 offset:1024
	ds_read_b128 v[10:13], v228 offset:2048
	ds_read_b128 v[14:17], v228 offset:3072
	ds_read_b128 v[134:137], v229
	ds_read_b128 v[138:141], v229 offset:1024
	ds_read_b128 v[142:145], v229 offset:2048
	ds_read_b128 v[146:149], v229 offset:3072
	s_mov_b32 m0, s59
	s_add_i32 s92, s56, 0x158000
	ds_read_b128 v[18:21], v227 offset:32768
	ds_read_b128 v[22:25], v227 offset:33792
	ds_read_b128 v[26:29], v227 offset:34816
	ds_read_b128 v[30:33], v227 offset:35840
	ds_read_b128 v[34:37], v227 offset:36864
	ds_read_b128 v[38:41], v227 offset:37888
	ds_read_b128 v[42:45], v227 offset:38912
	ds_read_b128 v[46:49], v227 offset:39936
	buffer_load_dwordx4 v223, s[12:15], s92 offen lds
	s_mov_b32 m0, s60
	s_add_i32 s92, s56, 0x204000
	buffer_load_dwordx4 v223, s[12:15], s92 offen lds
	s_waitcnt vmcnt(8) lgkmcnt(0)
	s_setprio 1
	s_barrier
	v_mfma_f32_16x16x128_f8f6f4 v[126:129], v[2:9], v[18:25], v[126:129]
	v_mfma_f32_16x16x128_f8f6f4 v[122:125], v[10:17], v[18:25], v[122:125]
	v_mfma_f32_16x16x128_f8f6f4 v[118:121], v[2:9], v[26:33], v[118:121]
	v_mfma_f32_16x16x128_f8f6f4 v[114:117], v[10:17], v[26:33], v[114:117]
	v_mfma_f32_16x16x128_f8f6f4 v[106:109], v[2:9], v[34:41], v[106:109]
	v_mfma_f32_16x16x128_f8f6f4 v[98:101], v[10:17], v[34:41], v[98:101]
	v_mfma_f32_16x16x128_f8f6f4 v[90:93], v[2:9], v[42:49], v[198:201]
	v_mfma_f32_16x16x128_f8f6f4 v[82:85], v[10:17], v[42:49], v[202:205]
	v_mfma_f32_16x16x128_f8f6f4 v[110:113], v[134:141], v[18:25], v[110:113]
	v_mfma_f32_16x16x128_f8f6f4 v[102:105], v[142:149], v[18:25], v[102:105]
	v_mfma_f32_16x16x128_f8f6f4 v[94:97], v[134:141], v[26:33], v[166:169]
	v_mfma_f32_16x16x128_f8f6f4 v[86:89], v[142:149], v[26:33], v[170:173]
	v_mfma_f32_16x16x128_f8f6f4 v[78:81], v[134:141], v[34:41], v[174:177]
	v_mfma_f32_16x16x128_f8f6f4 v[74:77], v[142:149], v[34:41], v[178:181]
	v_mfma_f32_16x16x128_f8f6f4 v[70:73], v[134:141], v[42:49], v[182:185]
	v_mfma_f32_16x16x128_f8f6f4 v[66:69], v[142:149], v[42:49], v[186:189]
	s_setprio 0
	s_barrier
	s_mov_b32 m0, s63
	s_or_b32 s92, s91, 0x80
	ds_read_b128 v[150:153], v227 offset:49152
	ds_read_b128 v[154:157], v227 offset:50176
	ds_read_b128 v[158:161], v227 offset:51200
	ds_read_b128 v[162:165], v227 offset:52224
	ds_read_b128 v[166:169], v227 offset:53248
	ds_read_b128 v[170:173], v227 offset:54272
	ds_read_b128 v[174:177], v227 offset:55296
	ds_read_b128 v[178:181], v227 offset:56320
	buffer_load_dwordx4 v224, s[16:19], s92 offen lds
	s_add_i32 s92, s91, 0xac080
	s_mov_b32 m0, s64
	s_add_i32 s56, s56, 0xac080
	buffer_load_dwordx4 v224, s[16:19], s92 offen lds
	s_add_i32 s92, s91, 0x158080
	s_mov_b32 m0, s67
	s_add_i32 s91, s91, 0x204080
	buffer_load_dwordx4 v224, s[16:19], s92 offen lds
	s_mov_b32 m0, s68
	s_nop 0
	buffer_load_dwordx4 v224, s[16:19], s91 offen lds
	s_mov_b32 m0, s65
	s_nop 0
	buffer_load_dwordx4 v223, s[12:15], s57 offen lds
	s_mov_b32 m0, s66
	s_nop 0
	buffer_load_dwordx4 v223, s[12:15], s56 offen lds
	s_waitcnt vmcnt(8) lgkmcnt(0)
	s_setprio 1
	s_barrier
	v_mfma_f32_16x16x128_f8f6f4 v[62:65], v[2:9], v[150:157], v[62:65]
	v_mfma_f32_16x16x128_f8f6f4 v[58:61], v[10:17], v[150:157], v[58:61]
	v_mfma_f32_16x16x128_f8f6f4 v[54:57], v[2:9], v[158:165], v[54:57]
	v_mfma_f32_16x16x128_f8f6f4 v[50:53], v[10:17], v[158:165], v[50:53]
	v_mfma_f32_16x16x128_f8f6f4 v[42:45], v[2:9], v[166:173], v[190:193]
	v_mfma_f32_16x16x128_f8f6f4 v[34:37], v[10:17], v[166:173], v[194:197]
	v_mfma_f32_16x16x128_f8f6f4 v[26:29], v[2:9], v[174:181], v[206:209]
	v_mfma_f32_16x16x128_f8f6f4 v[18:21], v[10:17], v[174:181], v[210:213]
	v_mfma_f32_16x16x128_f8f6f4 v[46:49], v[134:141], v[150:157], v[214:217]
	v_mfma_f32_16x16x128_f8f6f4 v[38:41], v[142:149], v[150:157], v[218:221]
	v_mfma_f32_16x16x128_f8f6f4 v[30:33], v[134:141], v[158:165], v[234:237]
	v_mfma_f32_16x16x128_f8f6f4 v[22:25], v[142:149], v[158:165], v[238:241]
	v_mfma_f32_16x16x128_f8f6f4 v[14:17], v[134:141], v[166:173], v[242:245]
	v_mfma_f32_16x16x128_f8f6f4 v[10:13], v[142:149], v[166:173], v[246:249]
	v_mfma_f32_16x16x128_f8f6f4 v[6:9], v[134:141], v[174:181], v[250:253]
	v_mfma_f32_16x16x128_f8f6f4 v[2:5], v[142:149], v[174:181], v[130:133]
	s_setprio 0
	s_barrier
	s_add_i32 s55, s55, 2
	s_addk_i32 s8, 0x100
	s_addk_i32 s9, 0x100
	s_cmp_ge_i32 s55, s3
	s_cbranch_scc0 .LBB0_1567
	v_pk_mul_f32 v[208:209], v[128:129], s[50:51] op_sel_hi:[1,0]
	v_pk_mul_f32 v[210:211], v[126:127], s[50:51] op_sel_hi:[1,0]
	v_pk_mul_f32 v[212:213], v[124:125], s[50:51] op_sel_hi:[1,0]
	v_pk_mul_f32 v[122:123], v[122:123], s[50:51] op_sel_hi:[1,0]
	v_pk_mul_f32 v[220:221], v[112:113], s[50:51] op_sel_hi:[1,0]
	v_pk_mul_f32 v[218:219], v[110:111], s[50:51] op_sel_hi:[1,0]
	v_pk_mul_f32 v[216:217], v[104:105], s[50:51] op_sel_hi:[1,0]
	v_pk_mul_f32 v[214:215], v[102:103], s[50:51] op_sel_hi:[1,0]
	v_pk_mul_f32 v[206:207], v[120:121], s[50:51] op_sel_hi:[1,0]
	v_pk_mul_f32 v[146:147], v[118:119], s[50:51] op_sel_hi:[1,0]
	v_pk_mul_f32 v[204:205], v[116:117], s[50:51] op_sel_hi:[1,0]
	v_pk_mul_f32 v[144:145], v[114:115], s[50:51] op_sel_hi:[1,0]
	v_pk_mul_f32 v[148:149], v[96:97], s[50:51] op_sel_hi:[1,0]
	v_pk_mul_f32 v[154:155], v[94:95], s[50:51] op_sel_hi:[1,0]
	v_pk_mul_f32 v[202:203], v[88:89], s[50:51] op_sel_hi:[1,0]
	v_pk_mul_f32 v[200:201], v[86:87], s[50:51] op_sel_hi:[1,0]
	v_pk_mul_f32 v[198:199], v[108:109], s[50:51] op_sel_hi:[1,0]
	v_pk_mul_f32 v[152:153], v[106:107], s[50:51] op_sel_hi:[1,0]
	v_pk_mul_f32 v[196:197], v[100:101], s[50:51] op_sel_hi:[1,0]
	v_pk_mul_f32 v[150:151], v[98:99], s[50:51] op_sel_hi:[1,0]
	v_pk_mul_f32 v[156:157], v[80:81], s[50:51] op_sel_hi:[1,0]
	v_pk_mul_f32 v[162:163], v[78:79], s[50:51] op_sel_hi:[1,0]
	v_pk_mul_f32 v[194:195], v[76:77], s[50:51] op_sel_hi:[1,0]
	v_pk_mul_f32 v[192:193], v[74:75], s[50:51] op_sel_hi:[1,0]
	v_pk_mul_f32 v[190:191], v[92:93], s[50:51] op_sel_hi:[1,0]
	v_pk_mul_f32 v[160:161], v[90:91], s[50:51] op_sel_hi:[1,0]
	v_pk_mul_f32 v[188:189], v[84:85], s[50:51] op_sel_hi:[1,0]
	v_pk_mul_f32 v[158:159], v[82:83], s[50:51] op_sel_hi:[1,0]
	v_pk_mul_f32 v[164:165], v[72:73], s[50:51] op_sel_hi:[1,0]
	v_pk_mul_f32 v[170:171], v[70:71], s[50:51] op_sel_hi:[1,0]
	v_pk_mul_f32 v[186:187], v[68:69], s[50:51] op_sel_hi:[1,0]
	v_pk_mul_f32 v[184:185], v[66:67], s[50:51] op_sel_hi:[1,0]
	v_pk_mul_f32 v[182:183], v[64:65], s[50:51] op_sel_hi:[1,0]
	v_pk_mul_f32 v[168:169], v[62:63], s[50:51] op_sel_hi:[1,0]
	v_pk_mul_f32 v[180:181], v[60:61], s[50:51] op_sel_hi:[1,0]
	v_pk_mul_f32 v[166:167], v[58:59], s[50:51] op_sel_hi:[1,0]
	v_pk_mul_f32 v[172:173], v[48:49], s[50:51] op_sel_hi:[1,0]
	v_pk_mul_f32 v[178:179], v[46:47], s[50:51] op_sel_hi:[1,0]
	v_pk_mul_f32 v[176:177], v[40:41], s[50:51] op_sel_hi:[1,0]
	v_pk_mul_f32 v[174:175], v[38:39], s[50:51] op_sel_hi:[1,0]
	v_pk_mul_f32 v[142:143], v[56:57], s[50:51] op_sel_hi:[1,0]
	v_pk_mul_f32 v[140:141], v[54:55], s[50:51] op_sel_hi:[1,0]
	v_pk_mul_f32 v[138:139], v[52:53], s[50:51] op_sel_hi:[1,0]
	v_pk_mul_f32 v[134:135], v[50:51], s[50:51] op_sel_hi:[1,0]
	v_pk_mul_f32 v[136:137], v[32:33], s[50:51] op_sel_hi:[1,0]
	v_pk_mul_f32 v[128:129], v[30:31], s[50:51] op_sel_hi:[1,0]
	v_pk_mul_f32 v[126:127], v[24:25], s[50:51] op_sel_hi:[1,0]
	v_pk_mul_f32 v[124:125], v[22:23], s[50:51] op_sel_hi:[1,0]
	v_pk_mul_f32 v[102:103], v[44:45], s[50:51] op_sel_hi:[1,0]
	v_pk_mul_f32 v[100:101], v[42:43], s[50:51] op_sel_hi:[1,0]
	v_pk_mul_f32 v[98:99], v[36:37], s[50:51] op_sel_hi:[1,0]
	v_pk_mul_f32 v[94:95], v[34:35], s[50:51] op_sel_hi:[1,0]
	v_pk_mul_f32 v[96:97], v[16:17], s[50:51] op_sel_hi:[1,0]
	v_pk_mul_f32 v[92:93], v[14:15], s[50:51] op_sel_hi:[1,0]
	v_pk_mul_f32 v[90:91], v[12:13], s[50:51] op_sel_hi:[1,0]
	v_pk_mul_f32 v[88:89], v[10:11], s[50:51] op_sel_hi:[1,0]
	v_pk_mul_f32 v[86:87], v[28:29], s[50:51] op_sel_hi:[1,0]
	v_pk_mul_f32 v[84:85], v[26:27], s[50:51] op_sel_hi:[1,0]
	v_pk_mul_f32 v[82:83], v[20:21], s[50:51] op_sel_hi:[1,0]
	v_pk_mul_f32 v[78:79], v[18:19], s[50:51] op_sel_hi:[1,0]
	v_pk_mul_f32 v[80:81], v[8:9], s[50:51] op_sel_hi:[1,0]
	v_pk_mul_f32 v[76:77], v[6:7], s[50:51] op_sel_hi:[1,0]
	v_pk_mul_f32 v[74:75], v[4:5], s[50:51] op_sel_hi:[1,0]
	v_pk_mul_f32 v[72:73], v[2:3], s[50:51] op_sel_hi:[1,0]
	s_and_b64 vcc, exec, s[48:49]
	s_cbranch_vccz .LBB0_1570
